# mLSTM: S^T waves load the Qs t-tile once into the persistent fragment registers (skip duplicate hoisted reads)
# baseline (speedup 1.0000x reference)
; #define LAS __attribute__((address_space(3)))
; #define MFMA16(a, b, c) __builtin_amdgcn_mfma_f32_16x16x32_bf16((a), (b), (c), 0, 0, 0)
; #define LDS_BARRIER() do { asm volatile("s_waitcnt lgkmcnt(0)" ::: "memory"); __builtin_amdgcn_s_barrier(); asm volatile("" ::: "memory"); } while (0)
; __device__ __forceinline__ void mlstm_item(const Args& a, LAS unsigned char* L, bool sample, int b, int hh, int sl, bool dry = false) {
;     ...
;         {
;             typedef short v4i16_t __attribute__((ext_vector_type(4)));
;             v4i16_t tl[2], th[2]; bf16x8 Bv[5];
; #pragma unroll
;             for (int kti = 0; kti < 2; ++kti) { const int kt = 2 * wave + kti;
;                 tl[kti] = __builtin_amdgcn_ds_read_tr16_b64_v4i16((LAS v4i16_t*)(L + L_KS + (g * 8 + (lr >> 2)) * 528 + (kt * 16 + 4 * (lr & 3)) * 2));
;                 th[kti] = __builtin_amdgcn_ds_read_tr16_b64_v4i16((LAS v4i16_t*)(L + L_KS + (g * 8 + 4 + (lr >> 2)) * 528 + (kt * 16 + 4 * (lr & 3)) * 2)); }
; #pragma unroll
;             for (int vt = 0; vt < 5; ++vt) Bv[vt] = *(const LAS bf16x8*)(L + L_VTW + (vt * 16 + lr) * 80 + g * 16);
; #pragma unroll
;             for (int kti = 0; kti < 2; ++kti) { const bf16x8 A = (bf16x8){tl[kti][0], tl[kti][1], tl[kti][2], tl[kti][3], th[kti][0], th[kti][1], th[kti][2], th[kti][3]};
; #pragma unroll
;                 for (int vt = 0; vt < 5; ++vt) Cacc[kti][vt] = MFMA16(A, Bv[vt], Cacc[kti][vt] * dL); }
;         }
;         LDS_BARRIER();
;         {
;             const int tt = wave & 1, vt = wave >> 1, t = tt * 16 + lr;
;             const bf16x8 Bs = *(const LAS bf16x8*)(L + L_SS + t * 80 + g * 16);
;             const f32x4 z4 = (f32x4){0.f, 0.f, 0.f, 0.f};
;             const bf16x8 Av = *(const LAS bf16x8*)(L + L_VT + (vt * 16 + lr) * 80 + g * 16);
;             bf16x8 Af[8], Bf[8];
; #pragma unroll
;             for (int kk = 0; kk < 8; ++kk) { Af[kk] = *(const LAS bf16x8*)(L + L_CS + (vt * 16 + lr) * 528 + kk * 64 + g * 16); Bf[kk] = *(const LAS bf16x8*)(L + L_QS + t * 528 + kk * 64 + g * 16); }
.LBB0_661:
	s_andn2_b64 vcc, s[64:65], s[68:69]
	s_cbranch_vccnz .Lhq_skip
	ds_read_b128 v[190:193], v239
	ds_read_b128 v[194:197], v239 offset:32
	ds_read_b128 v[198:201], v239 offset:64
	ds_read_b128 v[202:205], v239 offset:96
	ds_read_b128 v[206:209], v239 offset:128
	ds_read_b128 v[210:213], v239 offset:160
	ds_read_b128 v[214:217], v239 offset:192
	ds_read_b128 v[218:221], v239 offset:224
.Lhq_skip:
	ds_read_b64_tr_b16 v[58:59], v97 offset:19008
	s_waitcnt lgkmcnt(1)
	ds_read_b64_tr_b16 v[56:57], v97 offset:16896
	ds_read_b64_tr_b16 v[116:117], v97 offset:16912
	ds_read_b64_tr_b16 v[118:119], v97 offset:19024
	ds_read_b128 v[120:123], v95 offset:40192
	ds_read_b128 v[124:127], v95 offset:41472
	ds_read_b128 v[128:131], v95 offset:42752
	ds_read_b128 v[132:135], v95 offset:44032
	ds_read_b128 v[136:139], v95 offset:45312
	v_pk_mul_f32 v[38:39], v[38:39], v[76:77] op_sel_hi:[1,0]
	v_pk_mul_f32 v[36:37], v[36:37], v[76:77] op_sel_hi:[1,0]
	v_pk_mul_f32 v[54:55], v[54:55], v[76:77] op_sel_hi:[1,0]
	v_pk_mul_f32 v[52:53], v[52:53], v[76:77] op_sel_hi:[1,0]
	v_pk_mul_f32 v[50:51], v[50:51], v[76:77] op_sel_hi:[1,0]
	v_pk_mul_f32 v[48:49], v[48:49], v[76:77] op_sel_hi:[1,0]
	v_pk_mul_f32 v[46:47], v[46:47], v[76:77] op_sel_hi:[1,0]
	v_pk_mul_f32 v[44:45], v[44:45], v[76:77] op_sel_hi:[1,0]
	v_pk_mul_f32 v[42:43], v[42:43], v[76:77] op_sel_hi:[1,0]
	v_pk_mul_f32 v[40:41], v[40:41], v[76:77] op_sel_hi:[1,0]
	s_waitcnt lgkmcnt(4)
	v_mfma_f32_16x16x32_bf16 v[36:39], v[56:59], v[120:123], v[36:39]
	v_mul_f32_e64 v34, v34, v76
	v_mul_f32_e64 v35, v35, v76
	v_pk_mul_f32 v[32:33], v[32:33], v[76:77] op_sel_hi:[1,0]
	v_pk_mul_f32 v[30:31], v[30:31], v[76:77] op_sel_hi:[1,0]
	s_waitcnt lgkmcnt(3)
	v_mfma_f32_16x16x32_bf16 v[52:55], v[56:59], v[124:127], v[52:55]
	v_mul_f32_e64 v28, v28, v76
	v_mul_f32_e64 v29, v29, v76
	v_pk_mul_f32 v[26:27], v[26:27], v[76:77] op_sel_hi:[1,0]
	v_pk_mul_f32 v[24:25], v[24:25], v[76:77] op_sel_hi:[1,0]
	s_waitcnt lgkmcnt(2)
	v_mfma_f32_16x16x32_bf16 v[48:51], v[56:59], v[128:131], v[48:51]
	v_mul_f32_e64 v22, v22, v76
	v_mul_f32_e64 v23, v23, v76
	v_pk_mul_f32 v[20:21], v[20:21], v[76:77] op_sel_hi:[1,0]
	v_pk_mul_f32 v[18:19], v[18:19], v[76:77] op_sel_hi:[1,0]
	s_waitcnt lgkmcnt(1)
	v_mfma_f32_16x16x32_bf16 v[44:47], v[56:59], v[132:135], v[44:47]
	v_mul_f32_e64 v16, v16, v76
	v_mul_f32_e64 v17, v17, v76
	s_waitcnt lgkmcnt(0)
	s_barrier
	s_add_u32 s98, s100, s70
	s_addc_u32 s99, s101, s71
	s_add_u32 s98, s98, 0x70000
	s_addc_u32 s99, s99, 0
	s_lshl_b32 m0, s55, 10
	s_nop 0
	global_load_lds_dwordx4 v229, s[98:99]
	s_add_u32 m0, m0, 0x2000
	s_nop 0
	global_load_lds_dwordx4 v230, s[98:99]
	s_add_u32 m0, m0, 0x2000
	s_nop 0
	global_load_lds_dwordx4 v231, s[98:99]
	s_add_u32 m0, m0, 0x2000
	s_nop 0
	global_load_lds_dwordx4 v232, s[98:99]
	s_cmp_lg_u32 s55, 0
	s_cbranch_scc1 .Ldma_skip_loop
	s_mov_b32 m0, 0x8000
	s_nop 0
	global_load_lds_dwordx4 v233, s[98:99]

; #define LAS __attribute__((address_space(3)))
; #define MFMA16(a, b, c) __builtin_amdgcn_mfma_f32_16x16x32_bf16((a), (b), (c), 0, 0, 0)
; __device__ __forceinline__ void mlstm_item(const Args& a, LAS unsigned char* L, bool sample, int b, int hh, int sl, bool dry = false) {
;     ...
;         if (wave < 4) {
;             const int st = wave >> 1, tt = wave & 1, t = tt * 16 + lr;
;             f32x4 s = (f32x4){0.f, 0.f, 0.f, 0.f};
;             if (!(st == 1 && tt == 0)) {
;                 bf16x8 Af[8], Bf[8];
; #pragma unroll
;                 for (int kk = 0; kk < 8; ++kk) { Af[kk] = *(const LAS bf16x8*)(L + L_KS + (st * 16 + lr) * 528 + kk * 64 + g * 16); Bf[kk] = *(const LAS bf16x8*)(L + L_QS + t * 528 + kk * 64 + g * 16); }
;                 __builtin_amdgcn_sched_barrier(0);
; #pragma unroll
;                 for (int kk = 0; kk < 8; ++kk) s = MFMA16(Af[kk], Bf[kk], s);
.LBB0_671:
	s_andn2_b64 vcc, exec, s[72:73]
	s_cbranch_vccnz .LBB0_661
	v_mov_b32_e32 v56, 0
	s_andn2_b64 vcc, exec, s[64:65]
	v_mov_b32_e32 v57, 0
	v_mov_b32_e32 v58, 0
	v_mov_b32_e32 v59, 0
	s_cbranch_vccnz .LBB0_674
	v_add_u32_e32 v164, v101, v222
	v_add_u32_e32 v172, v100, v222
	ds_read_b128 v[56:59], v164 offset:16896
	ds_read_b128 v[116:119], v164 offset:16928
	ds_read_b128 v[190:193], v172
	ds_read_b128 v[194:197], v172 offset:32
	ds_read_b128 v[128:131], v164 offset:16960
	ds_read_b128 v[132:135], v164 offset:16992
	ds_read_b128 v[198:201], v172 offset:64
	ds_read_b128 v[202:205], v172 offset:96
	ds_read_b128 v[144:147], v164 offset:17024
	ds_read_b128 v[148:151], v164 offset:17056
	ds_read_b128 v[206:209], v172 offset:128
	ds_read_b128 v[210:213], v172 offset:160
	ds_read_b128 v[160:163], v164 offset:17088
	ds_read_b128 v[164:167], v164 offset:17120
	ds_read_b128 v[214:217], v172 offset:192
	ds_read_b128 v[218:221], v172 offset:224
	s_waitcnt lgkmcnt(13)
	v_mfma_f32_16x16x32_bf16 v[56:59], v[56:59], v[190:193], 0
	s_waitcnt lgkmcnt(12)
	v_mfma_f32_16x16x32_bf16 v[56:59], v[116:119], v[194:197], v[56:59]
	s_waitcnt lgkmcnt(9)
	v_mfma_f32_16x16x32_bf16 v[56:59], v[128:131], v[198:201], v[56:59]
	s_waitcnt lgkmcnt(8)
	v_mfma_f32_16x16x32_bf16 v[56:59], v[132:135], v[202:205], v[56:59]
	s_waitcnt lgkmcnt(5)
	v_mfma_f32_16x16x32_bf16 v[56:59], v[144:147], v[206:209], v[56:59]
	s_waitcnt lgkmcnt(4)
	v_mfma_f32_16x16x32_bf16 v[56:59], v[148:151], v[210:213], v[56:59]
	s_waitcnt lgkmcnt(1)
	v_mfma_f32_16x16x32_bf16 v[56:59], v[160:163], v[214:217], v[56:59]
	s_waitcnt lgkmcnt(0)
	v_mfma_f32_16x16x32_bf16 v[56:59], v[164:167], v[218:221], v[56:59]
